# grid barriers: L1 invalidate (acquire) issued at arrival, overlapped with the arrival atomic, instead of after the release is observed
# speedup vs baseline: 1.0033x; 1.0033x over previous
.LBB0_114:
	s_cmp_gt_i32 s81, 1
	s_cselect_b64 s[4:5], -1, 0
	s_and_b64 s[0:1], s[0:1], s[4:5]
	s_andn2_b64 vcc, exec, s[0:1]
	s_mov_b32 s0, 0
	v_writelane_b32 v231, s0, 24
	s_cbranch_vccnz .LBB0_129
	s_waitcnt vmcnt(0) lgkmcnt(0)
	s_barrier
	v_readfirstlane_b32 s98, v146
	s_or_b32 s99, s98, s84
	v_writelane_b32 v229, s99, 52
	v_writelane_b32 v229, s22, 55
	v_writelane_b32 v229, s23, 54
	s_cmp_lg_u32 s98, 0
	s_cbranch_scc1 .Lg0_done
	s_mov_b64 s[0:1], exec
	s_mov_b64 exec, 1
	buffer_wbl2 sc1
	s_waitcnt vmcnt(0)
	buffer_inv sc1
	v_mov_b32_e32 v2, 0
	s_cmp_lg_u32 s84, 0
	s_cbranch_scc1 .Lg0_wait
	v_mov_b32_e32 v0, 0x5ea0b001
	global_atomic_add v2, v0, s[22:23]
	s_waitcnt vmcnt(0)

.Lg0_rel:
	s_mov_b64 exec, s[0:1]

; __device__ __forceinline__ unsigned xb_ld(unsigned* p)              { return __hip_atomic_load(p, __ATOMIC_RELAXED, __HIP_MEMORY_SCOPE_AGENT); }
; __device__ __forceinline__ unsigned xb_add(unsigned* p, unsigned v) { return __hip_atomic_fetch_add(p, v, __ATOMIC_RELAXED, __HIP_MEMORY_SCOPE_AGENT); }
; #define XB_SPIN(cond, bar) do { unsigned _sp = 0; while (cond) { __builtin_amdgcn_s_sleep(1); \
;     if ((++_sp & 255u) == 0u) { if (xb_ld(&(bar)[XB_TMO])) break; if (_sp > XB_SPIN_CAP) { atomicAdd(&(bar)[XB_TMO], 1u); break; } } } } while (0)
; __device__ __forceinline__ void xcd_barrier(const XcdBarrier& b) {
;     ...
;         const unsigned old = xb_add(&bar[XB_XSUB(b.x)], 1u);
;         const unsigned gen = old / nloc;
;         if (old + 1u == (gen + 1u) * nloc) {
;             __builtin_amdgcn_fence(__ATOMIC_RELEASE, "agent");
;             asm volatile("s_waitcnt vmcnt(0)" ::: "memory");
;             const unsigned og = xb_add(&bar[XB_TOP], 1u);
;             const unsigned tg = og / nx;
;             if (og + 1u == (tg + 1u) * nx) xb_add(&bar[XB_TOPGEN], 1u);
;             else XB_SPIN(xb_ld(&bar[XB_TOPGEN]) == tg, bar);
;             __builtin_amdgcn_fence(__ATOMIC_ACQUIRE, "agent");
;             xb_add(&bar[XB_XGEN(b.x)], 1u);
;             asm volatile("s_waitcnt vmcnt(0)" ::: "memory");
;         } else {
;             XB_SPIN(xb_ld(&bar[XB_XGEN(b.x)]) == gen, bar);
.LBB0_163:
	v_readlane_b32 s0, v231, 24
	s_lshl_b32 s0, s0, 8
	s_add_u32 s0, s22, s0
	s_addc_u32 s1, s23, 0
	v_mov_b32_e32 v1, 0x1000
	v_mov_b32_e32 v3, 1
	global_atomic_add v3, v1, v3, s[0:1] offset:1024 sc0
	buffer_inv sc1
	v_cvt_f32_u32_e32 v1, v2
	v_sub_u32_e32 v4, 0, v2
	v_rcp_iflag_f32_e32 v1, v1
	s_nop 0
	v_mul_f32_e32 v1, 0x4f7ffffe, v1
	v_cvt_u32_f32_e32 v1, v1
	v_mul_lo_u32 v4, v4, v1
	v_mul_hi_u32 v4, v1, v4
	v_add_u32_e32 v1, v1, v4
	s_waitcnt vmcnt(0)
	v_mul_hi_u32 v1, v3, v1
	v_mul_lo_u32 v4, v1, v2
	v_sub_u32_e32 v4, v3, v4
	v_add_u32_e32 v5, 1, v1
	v_cmp_ge_u32_e32 vcc, v4, v2
	v_add_u32_e32 v3, 1, v3
	s_nop 0
	v_cndmask_b32_e32 v1, v1, v5, vcc
	v_sub_u32_e32 v5, v4, v2
	v_cndmask_b32_e32 v4, v4, v5, vcc
	v_add_u32_e32 v5, 1, v1
	v_cmp_ge_u32_e32 vcc, v4, v2
	s_nop 1
	v_cndmask_b32_e32 v1, v1, v5, vcc
	v_mul_lo_u32 v4, v2, v1
	v_add_u32_e32 v2, v4, v2
	v_cmp_ne_u32_e32 vcc, v3, v2
	s_and_saveexec_b64 s[8:9], vcc
	s_xor_b64 s[8:9], exec, s[8:9]
	s_cbranch_execz .LBB0_177
	s_waitcnt lgkmcnt(0)
	v_mov_b32_e32 v0, 0x2000
	global_load_dword v0, v0, s[0:1] offset:1024 sc1
	s_add_u32 s12, s0, 0x2400
	s_addc_u32 s13, s1, 0
	s_waitcnt vmcnt(0)
	v_cmp_eq_u32_e32 vcc, v0, v1
	s_and_saveexec_b64 s[10:11], vcc
	s_cbranch_execz .LBB0_176
	s_mov_b32 s3, 1
	s_mov_b64 s[14:15], 0
	v_mov_b32_e32 v0, 0
	s_branch .LBB0_167

; __device__ __forceinline__ unsigned xb_ld(unsigned* p)              { return __hip_atomic_load(p, __ATOMIC_RELAXED, __HIP_MEMORY_SCOPE_AGENT); }
; #define XB_SPIN(cond, bar) do { unsigned _sp = 0; while (cond) { __builtin_amdgcn_s_sleep(1); \
;     if ((++_sp & 255u) == 0u) { if (xb_ld(&(bar)[XB_TMO])) break; if (_sp > XB_SPIN_CAP) { atomicAdd(&(bar)[XB_TMO], 1u); break; } } } } while (0)
; __device__ __forceinline__ void xcd_barrier(const XcdBarrier& b) {
;     ...
;             XB_SPIN(xb_ld(&bar[XB_XGEN(b.x)]) == gen, bar);
;             __builtin_amdgcn_fence(__ATOMIC_ACQUIRE, "agent");
;             asm volatile("s_waitcnt vmcnt(0)" ::: "memory");
.LBB0_176:
	s_or_b64 exec, exec, s[10:11]
	s_waitcnt vmcnt(0)
	s_waitcnt vmcnt(0)

; __device__ __forceinline__ unsigned xb_add(unsigned* p, unsigned v) { return __hip_atomic_fetch_add(p, v, __ATOMIC_RELAXED, __HIP_MEMORY_SCOPE_AGENT); }
; __device__ __forceinline__ void xcd_barrier(const XcdBarrier& b) {
;     ...
;             __builtin_amdgcn_fence(__ATOMIC_ACQUIRE, "agent");
;             xb_add(&bar[XB_XGEN(b.x)], 1u);
;             asm volatile("s_waitcnt vmcnt(0)" ::: "memory");
.LBB0_194:
	s_or_b64 exec, exec, s[8:9]
	v_mov_b32_e32 v0, 0x2000
	v_mov_b32_e32 v1, 1
	s_waitcnt vmcnt(0)
	global_atomic_add v0, v1, s[0:1] offset:1024
	s_waitcnt vmcnt(0)

; __device__ __forceinline__ unsigned xb_ld(unsigned* p)              { return __hip_atomic_load(p, __ATOMIC_RELAXED, __HIP_MEMORY_SCOPE_AGENT); }
; __device__ __forceinline__ unsigned xb_add(unsigned* p, unsigned v) { return __hip_atomic_fetch_add(p, v, __ATOMIC_RELAXED, __HIP_MEMORY_SCOPE_AGENT); }
; #define XB_SPIN(cond, bar) do { unsigned _sp = 0; while (cond) { __builtin_amdgcn_s_sleep(1); \
;     if ((++_sp & 255u) == 0u) { if (xb_ld(&(bar)[XB_TMO])) break; if (_sp > XB_SPIN_CAP) { atomicAdd(&(bar)[XB_TMO], 1u); break; } } } } while (0)
; __device__ __forceinline__ void xcd_barrier(const XcdBarrier& b) {
;     ...
;         const unsigned old = xb_add(&bar[XB_XSUB(b.x)], 1u);
;         const unsigned gen = old / nloc;
;         if (old + 1u == (gen + 1u) * nloc) {
;             __builtin_amdgcn_fence(__ATOMIC_RELEASE, "agent");
;             asm volatile("s_waitcnt vmcnt(0)" ::: "memory");
;             const unsigned og = xb_add(&bar[XB_TOP], 1u);
;             const unsigned tg = og / nx;
;             if (og + 1u == (tg + 1u) * nx) xb_add(&bar[XB_TOPGEN], 1u);
;             else XB_SPIN(xb_ld(&bar[XB_TOPGEN]) == tg, bar);
;             __builtin_amdgcn_fence(__ATOMIC_ACQUIRE, "agent");
;             xb_add(&bar[XB_XGEN(b.x)], 1u);
;             asm volatile("s_waitcnt vmcnt(0)" ::: "memory");
;         } else {
;             XB_SPIN(xb_ld(&bar[XB_XGEN(b.x)]) == gen, bar);
.LBB0_389:
	v_readlane_b32 s2, v231, 24
	s_lshl_b32 s3, s2, 8
	s_add_u32 s6, s22, s3
	s_addc_u32 s7, s23, 0
	v_mov_b32_e32 v1, 0x1000
	v_mov_b32_e32 v3, 1
	global_atomic_add v3, v1, v3, s[6:7] offset:1024 sc0
	buffer_inv sc1
	v_cvt_f32_u32_e32 v1, v2
	v_sub_u32_e32 v4, 0, v2
	v_rcp_iflag_f32_e32 v1, v1
	s_nop 0
	v_mul_f32_e32 v1, 0x4f7ffffe, v1
	v_cvt_u32_f32_e32 v1, v1
	v_mul_lo_u32 v4, v4, v1
	v_mul_hi_u32 v4, v1, v4
	v_add_u32_e32 v1, v1, v4
	s_waitcnt vmcnt(0)
	v_mul_hi_u32 v1, v3, v1
	v_mul_lo_u32 v4, v1, v2
	v_sub_u32_e32 v4, v3, v4
	v_add_u32_e32 v5, 1, v1
	v_cmp_ge_u32_e32 vcc, v4, v2
	v_add_u32_e32 v3, 1, v3
	s_nop 0
	v_cndmask_b32_e32 v1, v1, v5, vcc
	v_sub_u32_e32 v5, v4, v2
	v_cndmask_b32_e32 v4, v4, v5, vcc
	v_add_u32_e32 v5, 1, v1
	v_cmp_ge_u32_e32 vcc, v4, v2
	s_nop 1
	v_cndmask_b32_e32 v1, v1, v5, vcc
	v_mul_lo_u32 v4, v2, v1
	v_add_u32_e32 v2, v4, v2
	v_cmp_ne_u32_e32 vcc, v3, v2
	s_and_saveexec_b64 s[8:9], vcc
	s_xor_b64 s[8:9], exec, s[8:9]
	s_cbranch_execz .LBB0_403
	s_waitcnt lgkmcnt(0)
	v_mov_b32_e32 v0, 0x2000
	global_load_dword v0, v0, s[6:7] offset:1024 sc1
	s_add_u32 s12, s6, 0x2400
	s_addc_u32 s13, s7, 0
	s_waitcnt vmcnt(0)
	v_cmp_eq_u32_e32 vcc, v0, v1
	s_and_saveexec_b64 s[10:11], vcc
	s_cbranch_execz .LBB0_402
	s_mov_b32 s3, 1
	s_mov_b64 s[14:15], 0
	v_mov_b32_e32 v0, 0
	s_branch .LBB0_393

; __device__ __forceinline__ unsigned xb_add(unsigned* p, unsigned v) { return __hip_atomic_fetch_add(p, v, __ATOMIC_RELAXED, __HIP_MEMORY_SCOPE_AGENT); }
; __device__ __forceinline__ void xcd_barrier(const XcdBarrier& b) {
;     ...
;             __builtin_amdgcn_fence(__ATOMIC_ACQUIRE, "agent");
;             xb_add(&bar[XB_XGEN(b.x)], 1u);
;             asm volatile("s_waitcnt vmcnt(0)" ::: "memory");
.LBB0_420:
	s_or_b64 exec, exec, s[8:9]
	v_mov_b32_e32 v0, 0x2000
	v_mov_b32_e32 v1, 1
	s_waitcnt vmcnt(0)
	global_atomic_add v0, v1, s[6:7] offset:1024
	s_waitcnt vmcnt(0)
